# decode per-head path: permlane32_swap for the cross-half ssq sum, partner-score reads issued together, exp2 chains of the 4 score rows interleaved
# speedup vs baseline: 1.0040x; 1.0020x over previous
.LBB0_1554:
	s_waitcnt lgkmcnt(0)
	s_barrier
	s_and_b64 vcc, exec, s[6:7]
	s_cbranch_vccnz .LBB0_1543
	ds_read_b32 v3, v4 offset:1024
	ds_read2st64_b32 v[246:247], v4 offset1:1
	ds_read2st64_b32 v[248:249], v4 offset0:2 offset1:3
	v_mov_b32_e32 v16, v7
	v_mov_b32_e32 v17, v7
	v_mov_b32_e32 v8, v7
	v_mov_b32_e32 v9, v7
	s_waitcnt lgkmcnt(2)
	v_add_f32_e32 v2, v2, v3
	v_fmamk_f32 v2, v2, 0x3c800000, v232
	v_rsq_f32_e32 v6, v2
	v_mov_b32_e32 v10, v7
	v_mov_b32_e32 v11, v7
	v_mov_b32_e32 v12, v7
	s_waitcnt lgkmcnt(1)
	v_pk_add_f32 v[2:3], v[114:115], v[246:247]
	s_waitcnt lgkmcnt(0)
	v_pk_add_f32 v[4:5], v[116:117], v[248:249]
	v_pk_mul_f32 v[2:3], v[2:3], v[6:7] op_sel_hi:[1,0]
	v_pk_mul_f32 v[4:5], v[6:7], v[4:5] op_sel_hi:[0,1]
	v_mov_b32_e32 v6, v7
	v_mov_b32_e32 v13, v7
	v_mov_b32_e32 v14, v7
	v_mov_b32_e32 v15, v7
	v_mov_b64_e32 v[112:113], v[16:17]
	v_mov_b64_e32 v[110:111], v[14:15]
	v_mov_b64_e32 v[108:109], v[12:13]
	v_mov_b64_e32 v[106:107], v[10:11]
	v_mov_b64_e32 v[104:105], v[8:9]
	v_mov_b64_e32 v[102:103], v[6:7]
	v_mov_b64_e32 v[100:101], v[4:5]
	v_mov_b64_e32 v[98:99], v[2:3]
	v_mul_lo_u32 v2, v244, s81
	v_lshl_or_b32 v2, v243, 1, v2
	v_mfma_f32_32x32x16_bf16 v[98:113], v[222:225], v[130:133], v[98:113]
	s_add_i32 s0, s11, s93
	v_add_u32_e32 v2, s0, v2
	v_add_u32_e32 v3, 0x25600, v2
	v_mfma_f32_32x32x16_bf16 v[98:113], v[218:221], v[134:137], v[98:113]
	s_nop 11
	v_sub_f32_e32 v4, v98, v230
	v_sub_f32_e32 v246, v99, v230
	v_cmp_gt_f32_e32 vcc, s31, v4
	v_sub_f32_e32 v247, v100, v230
	v_sub_f32_e32 v248, v101, v230
	v_cndmask_b32_e32 v5, 0, v233, vcc
	v_cndmask_b32_e32 v249, 0, v241, vcc
	v_cmp_gt_f32_e32 vcc, s31, v246
	v_add_f32_e32 v4, v4, v5
	v_exp_f32_e32 v4, v4
	v_cndmask_b32_e32 v5, 0, v233, vcc
	v_cndmask_b32_e32 v245, 0, v241, vcc
	v_cmp_gt_f32_e32 vcc, s31, v247
	v_add_f32_e32 v246, v246, v5
	v_exp_f32_e32 v246, v246
	v_ldexp_f32 v4, v4, v249
	v_cndmask_b32_e32 v5, 0, v233, vcc
	v_cndmask_b32_e32 v249, 0, v241, vcc
	v_cmp_gt_f32_e32 vcc, s31, v248
	v_add_f32_e32 v247, v247, v5
	v_exp_f32_e32 v247, v247
	v_ldexp_f32 v246, v246, v245
	v_cndmask_b32_e32 v5, 0, v233, vcc
	v_cndmask_b32_e32 v245, 0, v241, vcc
	v_add_f32_e32 v248, v248, v5
	v_exp_f32_e32 v248, v248
	v_cvt_pk_bf16_f32 v4, v4, v7
	ds_write_b16 v3, v4
	v_ldexp_f32 v247, v247, v249
	v_cvt_pk_bf16_f32 v246, v246, v7
	v_add_u32_e32 v5, 0x25710, v2
	ds_write_b16 v5, v246
	v_ldexp_f32 v248, v248, v245
	v_cvt_pk_bf16_f32 v247, v247, v7
	v_add_u32_e32 v249, 0x25820, v2
	ds_write_b16 v249, v247
	v_cvt_pk_bf16_f32 v248, v248, v7
	v_add_u32_e32 v2, 0x25930, v2
	ds_write_b16 v2, v248
	s_branch .LBB0_1543

.LBB0_1568:
	s_waitcnt lgkmcnt(0)
	s_barrier
	s_and_b64 vcc, exec, s[6:7]
	s_cbranch_vccnz .LBB0_1557
	ds_read_b32 v3, v4 offset:1024
	ds_read2st64_b32 v[246:247], v4 offset1:1
	ds_read2st64_b32 v[248:249], v4 offset0:2 offset1:3
	v_mov_b32_e32 v16, v7
	v_mov_b32_e32 v17, v7
	v_mov_b32_e32 v8, v7
	v_mov_b32_e32 v9, v7
	s_waitcnt lgkmcnt(2)
	v_add_f32_e32 v2, v2, v3
	v_fmamk_f32 v2, v2, 0x3c800000, v232
	v_rsq_f32_e32 v6, v2
	v_mov_b32_e32 v10, v7
	v_mov_b32_e32 v11, v7
	v_mov_b32_e32 v12, v7
	s_waitcnt lgkmcnt(1)
	v_pk_add_f32 v[2:3], v[114:115], v[246:247]
	s_waitcnt lgkmcnt(0)
	v_pk_add_f32 v[4:5], v[116:117], v[248:249]
	v_pk_mul_f32 v[2:3], v[2:3], v[6:7] op_sel_hi:[1,0]
	v_pk_mul_f32 v[4:5], v[6:7], v[4:5] op_sel_hi:[0,1]
	v_mov_b32_e32 v6, v7
	v_mov_b32_e32 v13, v7
	v_mov_b32_e32 v14, v7
	v_mov_b32_e32 v15, v7
	v_mov_b64_e32 v[112:113], v[16:17]
	v_mov_b64_e32 v[110:111], v[14:15]
	v_mov_b64_e32 v[108:109], v[12:13]
	v_mov_b64_e32 v[106:107], v[10:11]
	v_mov_b64_e32 v[104:105], v[8:9]
	v_mov_b64_e32 v[102:103], v[6:7]
	v_mov_b64_e32 v[100:101], v[4:5]
	v_mov_b64_e32 v[98:99], v[2:3]
	v_mul_lo_u32 v2, v244, s81
	v_lshl_or_b32 v2, v243, 1, v2
	v_mfma_f32_32x32x16_bf16 v[98:113], v[222:225], v[130:133], v[98:113]
	s_add_i32 s0, s13, s93
	v_add_u32_e32 v2, s0, v2
	v_add_u32_e32 v3, 0x27800, v2
	v_mfma_f32_32x32x16_bf16 v[98:113], v[218:221], v[134:137], v[98:113]
	s_nop 11
	v_sub_f32_e32 v4, v98, v230
	v_sub_f32_e32 v246, v99, v230
	v_cmp_gt_f32_e32 vcc, s31, v4
	v_sub_f32_e32 v247, v100, v230
	v_sub_f32_e32 v248, v101, v230
	v_cndmask_b32_e32 v5, 0, v233, vcc
	v_cndmask_b32_e32 v249, 0, v241, vcc
	v_cmp_gt_f32_e32 vcc, s31, v246
	v_add_f32_e32 v4, v4, v5
	v_exp_f32_e32 v4, v4
	v_cndmask_b32_e32 v5, 0, v233, vcc
	v_cndmask_b32_e32 v245, 0, v241, vcc
	v_cmp_gt_f32_e32 vcc, s31, v247
	v_add_f32_e32 v246, v246, v5
	v_exp_f32_e32 v246, v246
	v_ldexp_f32 v4, v4, v249
	v_cndmask_b32_e32 v5, 0, v233, vcc
	v_cndmask_b32_e32 v249, 0, v241, vcc
	v_cmp_gt_f32_e32 vcc, s31, v248
	v_add_f32_e32 v247, v247, v5
	v_exp_f32_e32 v247, v247
	v_ldexp_f32 v246, v246, v245
	v_cndmask_b32_e32 v5, 0, v233, vcc
	v_cndmask_b32_e32 v245, 0, v241, vcc
	v_add_f32_e32 v248, v248, v5
	v_exp_f32_e32 v248, v248
	v_cvt_pk_bf16_f32 v4, v4, v7
	ds_write_b16 v3, v4
	v_ldexp_f32 v247, v247, v249
	v_cvt_pk_bf16_f32 v246, v246, v7
	v_add_u32_e32 v5, 0x27910, v2
	ds_write_b16 v5, v246
	v_ldexp_f32 v248, v248, v245
	v_cvt_pk_bf16_f32 v247, v247, v7
	v_add_u32_e32 v249, 0x27a20, v2
	ds_write_b16 v249, v247
	v_cvt_pk_bf16_f32 v248, v248, v7
	v_add_u32_e32 v2, 0x27b30, v2
	ds_write_b16 v2, v248
	s_branch .LBB0_1557

.LBB0_1598:
	s_waitcnt lgkmcnt(0)
	s_barrier
	s_and_b64 vcc, exec, s[6:7]
	s_cbranch_vccnz .LBB0_1587
	ds_read_b32 v3, v4 offset:1024
	ds_read2st64_b32 v[246:247], v4 offset1:1
	ds_read2st64_b32 v[248:249], v4 offset0:2 offset1:3
	v_mov_b32_e32 v16, v7
	v_mov_b32_e32 v17, v7
	v_mov_b32_e32 v8, v7
	v_mov_b32_e32 v9, v7
	s_waitcnt lgkmcnt(2)
	v_add_f32_e32 v2, v2, v3
	v_fmamk_f32 v2, v2, 0x3c800000, v232
	v_rsq_f32_e32 v6, v2
	v_mov_b32_e32 v10, v7
	v_mov_b32_e32 v11, v7
	v_mov_b32_e32 v12, v7
	s_waitcnt lgkmcnt(1)
	v_pk_add_f32 v[2:3], v[114:115], v[246:247]
	s_waitcnt lgkmcnt(0)
	v_pk_add_f32 v[4:5], v[116:117], v[248:249]
	v_pk_mul_f32 v[2:3], v[2:3], v[6:7] op_sel_hi:[1,0]
	v_pk_mul_f32 v[4:5], v[6:7], v[4:5] op_sel_hi:[0,1]
	v_mov_b32_e32 v6, v7
	v_mov_b32_e32 v13, v7
	v_mov_b32_e32 v14, v7
	v_mov_b32_e32 v15, v7
	v_mov_b64_e32 v[112:113], v[16:17]
	v_mov_b64_e32 v[110:111], v[14:15]
	v_mov_b64_e32 v[108:109], v[12:13]
	v_mov_b64_e32 v[106:107], v[10:11]
	v_mov_b64_e32 v[104:105], v[8:9]
	v_mov_b64_e32 v[102:103], v[6:7]
	v_mov_b64_e32 v[100:101], v[4:5]
	v_mov_b64_e32 v[98:99], v[2:3]
	v_mul_lo_u32 v2, v244, s81
	v_lshl_or_b32 v2, v243, 1, v2
	v_mfma_f32_32x32x16_bf16 v[98:113], v[222:225], v[130:133], v[98:113]
	s_add_i32 s0, s92, s93
	v_add_u32_e32 v2, s0, v2
	v_add_u32_e32 v3, 0x25600, v2
	v_mfma_f32_32x32x16_bf16 v[98:113], v[218:221], v[134:137], v[98:113]
	s_nop 11
	v_sub_f32_e32 v4, v98, v230
	v_sub_f32_e32 v246, v99, v230
	v_cmp_gt_f32_e32 vcc, s31, v4
	v_sub_f32_e32 v247, v100, v230
	v_sub_f32_e32 v248, v101, v230
	v_cndmask_b32_e32 v5, 0, v233, vcc
	v_cndmask_b32_e32 v249, 0, v241, vcc
	v_cmp_gt_f32_e32 vcc, s31, v246
	v_add_f32_e32 v4, v4, v5
	v_exp_f32_e32 v4, v4
	v_cndmask_b32_e32 v5, 0, v233, vcc
	v_cndmask_b32_e32 v245, 0, v241, vcc
	v_cmp_gt_f32_e32 vcc, s31, v247
	v_add_f32_e32 v246, v246, v5
	v_exp_f32_e32 v246, v246
	v_ldexp_f32 v4, v4, v249
	v_cndmask_b32_e32 v5, 0, v233, vcc
	v_cndmask_b32_e32 v249, 0, v241, vcc
	v_cmp_gt_f32_e32 vcc, s31, v248
	v_add_f32_e32 v247, v247, v5
	v_exp_f32_e32 v247, v247
	v_ldexp_f32 v246, v246, v245
	v_cndmask_b32_e32 v5, 0, v233, vcc
	v_cndmask_b32_e32 v245, 0, v241, vcc
	v_add_f32_e32 v248, v248, v5
	v_exp_f32_e32 v248, v248
	v_cvt_pk_bf16_f32 v4, v4, v7
	ds_write_b16 v3, v4
	v_ldexp_f32 v247, v247, v249
	v_cvt_pk_bf16_f32 v246, v246, v7
	v_add_u32_e32 v5, 0x25710, v2
	ds_write_b16 v5, v246
	v_ldexp_f32 v248, v248, v245
	v_cvt_pk_bf16_f32 v247, v247, v7
	v_add_u32_e32 v249, 0x25820, v2
	ds_write_b16 v249, v247
	v_cvt_pk_bf16_f32 v248, v248, v7
	v_add_u32_e32 v2, 0x25930, v2
	ds_write_b16 v2, v248
	s_branch .LBB0_1587

.LBB0_1628:
	s_waitcnt lgkmcnt(0)
	s_barrier
	s_and_b64 vcc, exec, s[6:7]
	s_cbranch_vccnz .LBB0_1617
	ds_read_b32 v3, v4 offset:1024
	ds_read2st64_b32 v[246:247], v4 offset1:1
	ds_read2st64_b32 v[248:249], v4 offset0:2 offset1:3
	v_mov_b32_e32 v16, v7
	v_mov_b32_e32 v17, v7
	v_mov_b32_e32 v8, v7
	v_mov_b32_e32 v9, v7
	s_waitcnt lgkmcnt(2)
	v_add_f32_e32 v2, v2, v3
	v_fmamk_f32 v2, v2, 0x3c800000, v232
	v_rsq_f32_e32 v6, v2
	v_mov_b32_e32 v10, v7
	v_mov_b32_e32 v11, v7
	v_mov_b32_e32 v12, v7
	s_waitcnt lgkmcnt(1)
	v_pk_add_f32 v[2:3], v[114:115], v[246:247]
	s_waitcnt lgkmcnt(0)
	v_pk_add_f32 v[4:5], v[116:117], v[248:249]
	v_pk_mul_f32 v[2:3], v[2:3], v[6:7] op_sel_hi:[1,0]
	v_pk_mul_f32 v[4:5], v[6:7], v[4:5] op_sel_hi:[0,1]
	v_mov_b32_e32 v6, v7
	v_mov_b32_e32 v13, v7
	v_mov_b32_e32 v14, v7
	v_mov_b32_e32 v15, v7
	v_mov_b64_e32 v[112:113], v[16:17]
	v_mov_b64_e32 v[110:111], v[14:15]
	v_mov_b64_e32 v[108:109], v[12:13]
	v_mov_b64_e32 v[106:107], v[10:11]
	v_mov_b64_e32 v[104:105], v[8:9]
	v_mov_b64_e32 v[102:103], v[6:7]
	v_mov_b64_e32 v[100:101], v[4:5]
	v_mov_b64_e32 v[98:99], v[2:3]
	v_mul_lo_u32 v2, v244, s81
	v_lshl_or_b32 v2, v243, 1, v2
	v_mfma_f32_32x32x16_bf16 v[98:113], v[222:225], v[130:133], v[98:113]
	s_add_i32 s0, s82, s93
	v_add_u32_e32 v2, s0, v2
	v_add_u32_e32 v3, 0x27800, v2
	v_mfma_f32_32x32x16_bf16 v[98:113], v[218:221], v[134:137], v[98:113]
	s_nop 11
	v_sub_f32_e32 v4, v98, v230
	v_sub_f32_e32 v246, v99, v230
	v_cmp_gt_f32_e32 vcc, s31, v4
	v_sub_f32_e32 v247, v100, v230
	v_sub_f32_e32 v248, v101, v230
	v_cndmask_b32_e32 v5, 0, v233, vcc
	v_cndmask_b32_e32 v249, 0, v241, vcc
	v_cmp_gt_f32_e32 vcc, s31, v246
	v_add_f32_e32 v4, v4, v5
	v_exp_f32_e32 v4, v4
	v_cndmask_b32_e32 v5, 0, v233, vcc
	v_cndmask_b32_e32 v245, 0, v241, vcc
	v_cmp_gt_f32_e32 vcc, s31, v247
	v_add_f32_e32 v246, v246, v5
	v_exp_f32_e32 v246, v246
	v_ldexp_f32 v4, v4, v249
	v_cndmask_b32_e32 v5, 0, v233, vcc
	v_cndmask_b32_e32 v249, 0, v241, vcc
	v_cmp_gt_f32_e32 vcc, s31, v248
	v_add_f32_e32 v247, v247, v5
	v_exp_f32_e32 v247, v247
	v_ldexp_f32 v246, v246, v245
	v_cndmask_b32_e32 v5, 0, v233, vcc
	v_cndmask_b32_e32 v245, 0, v241, vcc
	v_add_f32_e32 v248, v248, v5
	v_exp_f32_e32 v248, v248
	v_cvt_pk_bf16_f32 v4, v4, v7
	ds_write_b16 v3, v4
	v_ldexp_f32 v247, v247, v249
	v_cvt_pk_bf16_f32 v246, v246, v7
	v_add_u32_e32 v5, 0x27910, v2
	ds_write_b16 v5, v246
	v_ldexp_f32 v248, v248, v245
	v_cvt_pk_bf16_f32 v247, v247, v7
	v_add_u32_e32 v249, 0x27a20, v2
	ds_write_b16 v249, v247
	v_cvt_pk_bf16_f32 v248, v248, v7
	v_add_u32_e32 v2, 0x27b30, v2
	ds_write_b16 v2, v248
	s_branch .LBB0_1617
